# barrier 6 split by dependency: row-panel arrival word + same-XCD fast wait before the out-projection K-loop, grid barrier 6 awaited only before the final d_out stores (beside the ssq wait)
# speedup vs baseline: 1.0810x; 1.0039x over previous
; #define PG8_WAIT_V(n) asm volatile("s_waitcnt vmcnt(" #n ")" ::: "memory")
; #define PG8_BAR __builtin_amdgcn_s_barrier()
; __device__ __forceinline__ unsigned xb_ld(unsigned* p)              { return __hip_atomic_load(p, __ATOMIC_RELAXED, __HIP_MEMORY_SCOPE_AGENT); }
; template <class Epi, class Sched, bool ZERO>
; __device__ __forceinline__ void gemm_phase_acc(LAS unsigned char* lds, const Gemm g, const Sched& S, const Epi& E, f32x4 (&acc)[2][2][4][2]) {
;     ...
;     PG8_WAIT_V(0);
;     if (wr == 0) PG8_BAR;
;     PG8_BAR;
; __device__ __forceinline__ void xcd_barrier_complete(unsigned* bar, unsigned x, unsigned& nloc, unsigned& nx) {
;     const unsigned G = gridDim.x * gridDim.y * gridDim.z;
;     unsigned sum, cnt, mine, sp = 0u;
;     for (;;) {
;         sum = 0u; cnt = 0u; mine = 0u;
; #pragma unroll
;         for (unsigned j = 0; j < 16; ++j) { const unsigned c = xb_ld(&bar[XB_XCNT(j)]); sum += c; cnt += (c > 0u) ? 1u : 0u; mine = (j == x) ? c : mine; }
;         if (sum == G) break;
;         __builtin_amdgcn_s_sleep(1);
;         if ((++sp & 255u) == 0u) { if (xb_ld(&bar[XB_TMO])) break; if (sp > XB_SPIN_CAP) { atomicAdd(&bar[XB_TMO], 1u); break; } }
;     }
;     nloc = mine > 0u ? mine : 1u; nx = cnt > 0u ? cnt : 1u;
; }
; __device__ __forceinline__ void xcd_barrier(const XcdBarrier& b) {
;     asm volatile("s_waitcnt vmcnt(0)" ::: "memory");
;     __syncthreads();
;     if (threadIdx.x == 0) {
;         unsigned* bar = b.bar;
;         __builtin_amdgcn_s_waitcnt(0);
;         unsigned nloc = b.st[0], nx = b.st[1];
;         if (nloc == 0u) { xcd_barrier_complete(bar, b.x, nloc, nx); b.st[0] = nloc; b.st[1] = nx; }
.LBB0_982:
	s_barrier
	s_waitcnt vmcnt(0)
	s_lshl_b32 s54, s34, 8
	s_waitcnt lgkmcnt(0)
	s_barrier
	v_cmp_eq_u32_e32 vcc, 0, v224
	s_and_saveexec_b64 s[4:5], vcc
	s_cbranch_execz .Lpa6_skip
	v_readlane_b32 s2, v254, 5
	s_lshl_b32 s3, s2, 2
	s_lshl_b32 s3, 1, s3
	s_cmp_lt_u32 s2, 8
	s_cselect_b32 s3, s3, 0
	s_lshl_b32 s6, s18, 8
	s_add_u32 s6, s6, 0xff84080
	s_add_u32 s6, s70, s6
	s_addc_u32 s7, s71, 0
	v_mov_b32_e32 v0, 0
	v_mov_b32_e32 v1, s3
	global_atomic_add v0, v1, s[6:7]
.Lpa6_skip:
	s_or_b64 exec, exec, s[4:5]
	s_mov_b64 s[0:1], exec
	v_readlane_b32 s2, v254, 1
	v_readlane_b32 s3, v254, 2
	s_and_b64 s[2:3], s[0:1], s[2:3]
	s_mov_b64 exec, s[2:3]
	s_cbranch_execz .LBB0_1034
	s_add_i32 s2, 0, 0x25ff0
	v_mov_b32_e32 v0, s2
	s_waitcnt vmcnt(0) expcnt(0) lgkmcnt(0)
	ds_read_b32 v2, v0
	s_add_i32 s2, 0, 0x25ff4
	v_mov_b32_e32 v0, s2
	ds_read_b32 v0, v0
	s_waitcnt lgkmcnt(1)
	v_cmp_ne_u32_e32 vcc, 0, v2
	s_cbranch_vccnz .LBB0_998
	v_readlane_b32 s2, v254, 0
	s_mul_i32 s55, s73, s2
	s_add_u32 s2, s70, 0xff80200
	s_addc_u32 s3, s71, 0
	s_add_u32 s4, s70, 0xff80400
	s_addc_u32 s5, s71, 0
	s_add_u32 s6, s70, 0xff80500
	s_addc_u32 s7, s71, 0
	s_add_u32 s8, s70, 0xff80600
	s_addc_u32 s9, s71, 0
	s_add_u32 s10, s70, 0xff80700
	s_addc_u32 s11, s71, 0
	s_add_u32 s12, s70, 0xff80800
	s_addc_u32 s13, s71, 0
	s_add_u32 s14, s70, 0xff80900
	s_addc_u32 s15, s71, 0
	s_add_u32 s16, s70, 0xff80a00
	s_addc_u32 s17, s71, 0
	s_add_u32 s24, s70, 0xff80b00
	s_addc_u32 s25, s71, 0
	s_add_u32 s26, s70, 0xff80c00
	s_addc_u32 s27, s71, 0
	s_add_u32 s28, s70, 0xff80d00
	s_addc_u32 s29, s71, 0
	s_add_u32 s30, s70, 0xff80e00
	s_addc_u32 s31, s71, 0
	s_add_u32 s38, s70, 0xff80f00
	s_addc_u32 s39, s71, 0
	s_add_u32 s40, s70, 0xff81000
	s_addc_u32 s41, s71, 0
	s_add_u32 s42, s70, 0xff81100
	s_addc_u32 s43, s71, 0
	s_add_u32 s44, s70, 0xff81200
	s_addc_u32 s45, s71, 0
	s_add_u32 s46, s70, 0xff81300
	s_mul_i32 s55, s55, s72
	s_addc_u32 s47, s71, 0
	s_mov_b32 s56, 1
	v_mov_b32_e32 v16, 0
	s_branch .LBB0_986

; __device__ __forceinline__ unsigned xb_ld(unsigned* p)              { return __hip_atomic_load(p, __ATOMIC_RELAXED, __HIP_MEMORY_SCOPE_AGENT); }
; __device__ __forceinline__ unsigned xb_add(unsigned* p, unsigned v) { return __hip_atomic_fetch_add(p, v, __ATOMIC_RELAXED, __HIP_MEMORY_SCOPE_AGENT); }
; #define XB_SPIN(cond, bar) do { unsigned _sp = 0; while (cond) { __builtin_amdgcn_s_sleep(1); \
;     if ((++_sp & 255u) == 0u) { if (xb_ld(&(bar)[XB_TMO])) break; if (_sp > XB_SPIN_CAP) { atomicAdd(&(bar)[XB_TMO], 1u); break; } } } } while (0)
; __device__ __forceinline__ void xcd_barrier(const XcdBarrier& b) {
;     ...
;         const unsigned old = xb_add(&bar[XB_XSUB(b.x)], 1u);
;         const unsigned gen = old / nloc;
;         if (old + 1u == (gen + 1u) * nloc) {
;             __builtin_amdgcn_fence(__ATOMIC_RELEASE, "agent");
;             asm volatile("s_waitcnt vmcnt(0)" ::: "memory");
;             const unsigned og = xb_add(&bar[XB_TOP], 1u);
;             const unsigned tg = og / nx;
;             if (og + 1u == (tg + 1u) * nx) xb_add(&bar[XB_TOPGEN], 1u);
;             else XB_SPIN(xb_ld(&bar[XB_TOPGEN]) == tg, bar);
;             __builtin_amdgcn_fence(__ATOMIC_ACQUIRE, "agent");
;             xb_add(&bar[XB_XGEN(b.x)], 1u);
;             asm volatile("s_waitcnt vmcnt(0)" ::: "memory");
;         } else {
;             XB_SPIN(xb_ld(&bar[XB_XGEN(b.x)]) == gen, bar);
;             __builtin_amdgcn_fence(__ATOMIC_ACQUIRE, "agent");
;             asm volatile("s_waitcnt vmcnt(0)" ::: "memory");
;         }
.LBB0_1034:
	s_or_b64 exec, exec, s[0:1]
	s_waitcnt lgkmcnt(0)
	v_mov_b32_e32 v0, v224
	v_cmp_eq_u32_e32 vcc, 0, v224
	s_and_saveexec_b64 s[44:45], vcc
	s_cbranch_execz .Lgb6_done
	s_add_u32 s40, s70, 0xff83500
	s_addc_u32 s41, s71, 0
	s_lshl_b32 s46, s18, 8
	s_add_u32 s46, s46, 0xff84080
	s_add_u32 s46, s70, s46
	s_addc_u32 s47, s71, 0
	v_readlane_b32 s48, v254, 5
	s_mov_b32 s50, 4
	s_cmp_lt_u32 s48, 8
	s_cselect_b32 s50, s50, 16
	s_lshl_b32 s48, s48, 2
	s_mov_b32 s42, 0x8000
	v_mov_b32_e32 v250, 0
.Lgb6_spin:
	global_load_dword v251, v250, s[46:47] sc1
	global_load_dword v252, v250, s[40:41] sc1
	s_waitcnt vmcnt(0)
	v_readfirstlane_b32 s43, v251
	v_readfirstlane_b32 s49, v252
	s_lshr_b32 s43, s43, s48
	s_and_b32 s43, s43, 15
	s_cmp_ge_u32 s43, s50
	s_cbranch_scc1 .Lgb6_ok
	s_cmp_ge_u32 s49, 6
	s_cbranch_scc1 .Lgb6_ok
	s_sleep 1
	s_sub_u32 s42, s42, 1
	s_cmp_lg_u32 s42, 0
	s_cbranch_scc1 .Lgb6_spin

; __device__ __forceinline__ unsigned xb_ld(unsigned* p)              { return __hip_atomic_load(p, __ATOMIC_RELAXED, __HIP_MEMORY_SCOPE_AGENT); }
; __device__ __forceinline__ unsigned xb_add(unsigned* p, unsigned v) { return __hip_atomic_fetch_add(p, v, __ATOMIC_RELAXED, __HIP_MEMORY_SCOPE_AGENT); }
; #define XB_SPIN(cond, bar) do { unsigned _sp = 0; while (cond) { __builtin_amdgcn_s_sleep(1); \
;     if ((++_sp & 255u) == 0u) { if (xb_ld(&(bar)[XB_TMO])) break; if (_sp > XB_SPIN_CAP) { atomicAdd(&(bar)[XB_TMO], 1u); break; } } } } while (0)
; __device__ __forceinline__ void xcd_barrier(const XcdBarrier& b) {
;     ...
;             const unsigned og = xb_add(&bar[XB_TOP], 1u);
;             const unsigned tg = og / nx;
;             if (og + 1u == (tg + 1u) * nx) xb_add(&bar[XB_TOPGEN], 1u);
;             else XB_SPIN(xb_ld(&bar[XB_TOPGEN]) == tg, bar);
;             __builtin_amdgcn_fence(__ATOMIC_ACQUIRE, "agent");
;             xb_add(&bar[XB_XGEN(b.x)], 1u);
;             asm volatile("s_waitcnt vmcnt(0)" ::: "memory");
;         } else {
;             XB_SPIN(xb_ld(&bar[XB_XGEN(b.x)]) == gen, bar);
;             __builtin_amdgcn_fence(__ATOMIC_ACQUIRE, "agent");
;             asm volatile("s_waitcnt vmcnt(0)" ::: "memory");
.LBB0_1064:
	s_add_u32 s6, s70, 0xff83500
	s_addc_u32 s7, s71, 0
	s_mov_b32 s8, 0x8000
.Lgb6w_spin:
	global_load_dword v2, v1, s[6:7] sc1
	s_waitcnt vmcnt(0)
	v_readfirstlane_b32 s9, v2
	s_cmp_ge_u32 s9, 6
	s_cbranch_scc1 .Lgb6w_ok
	s_sleep 1
	s_sub_u32 s8, s8, 1
	s_cmp_lg_u32 s8, 0
	s_cbranch_scc1 .Lgb6w_spin
